# speedup vs baseline: 1.0015x; 1.0015x over previous
; template <int MODE>
; DI void attn_item(const u16* __restrict__ Qp, const u16* __restrict__ Kp, const u16* __restrict__ VTp, int q0,
;                   int kt_lo, int kt_hi, u16* __restrict__ Op, int os, float* __restrict__ lsep, int ls, char* lds, int tid) {
;     ...
;       float psum = 0.f;
; #pragma unroll
;       for (int mt = 0; mt < NMT; mt++)
; #pragma unroll
;         for (int r = 0; r < 16; r++) {
;           const float p = __builtin_amdgcn_exp2f(st[mt][r] - m_new);
;           psum += p;
;           st[mt][r] = p;
;         }
;       l_run = l_run * alpha + psum;
;     ...
;     if (PF) {
;       if (it + 1 < ntiles) { PF_STORE((it + 1) & 1) }
;       __syncthreads();
.LBB0_441:
	v_add_f32_e32 v66, 0, v66
	v_add_f32_e32 v66, v67, v66
	v_add_f32_e32 v66, v68, v66
	v_add_f32_e32 v66, v69, v66
	v_add_f32_e32 v66, v70, v66
	v_add_f32_e32 v66, v71, v66
	v_add_f32_e32 v66, v72, v66
	v_add_f32_e32 v66, v73, v66
	v_add_f32_e32 v66, v74, v66
	v_add_f32_e32 v66, v75, v66
	v_add_f32_e32 v66, v76, v66
	v_add_f32_e32 v66, v77, v66
	v_add_f32_e32 v66, v78, v66
	v_add_f32_e32 v66, v79, v66
	v_add_f32_e32 v66, v137, v66
	v_add_f32_e32 v66, v138, v66
	s_add_i32 s38, s38, 32
	v_fmac_f32_e32 v66, v136, v64
	s_cmp_eq_u32 s48, s49
	v_subrev_u32_e32 v134, 32, v134
	s_waitcnt lgkmcnt(0)
	s_barrier
	s_cbranch_scc1 .LBB0_444
	v_mov_b32_e32 v136, v66
	v_mov_b32_e32 v137, v65
	s_cmp_lt_i32 s49, s47
	s_cselect_b64 s[42:43], -1, 0
	s_cmp_ge_i32 s49, s47
	s_cbranch_scc1 .LBB0_439
	s_branch .LBB0_438
